# G1 unit-order split by odd/even XCD instead of XCD halves (odd XCDs run heavy-epilogue units first)
# speedup vs baseline: 1.0580x; 1.0025x over previous
.LBB0_185:
	s_and_b64 s[0:1], s[78:79], exec
	v_readlane_b32 s0, v235, 27
	v_readlane_b32 s1, v235, 28
	v_readlane_b32 s6, v236, 12
	s_cselect_b32 s57, s0, s1
	v_readlane_b32 s0, v235, 29
	v_readlane_b32 s1, v235, 30
	v_mov_b32_e32 v8, v194
	v_readlane_b32 s7, v236, 13
	s_cselect_b32 s58, s0, s1
	v_cmp_ne_u32_e64 s[0:1], 1, v196
	s_andn2_b64 vcc, exec, s[6:7]
	v_readfirstlane_b32 s16, v8
	s_cbranch_vccnz .LBB0_187
	s_and_b64 s[8:9], s[78:79], exec
	v_readlane_b32 s6, v234, 19
	s_cselect_b32 s8, 20, 19
	v_readlane_b32 s7, v234, 20
	s_lshl_b64 s[8:9], s[6:7], s8
	s_add_u32 s40, s84, s8
	s_addc_u32 s41, s85, s9
	v_readlane_b32 s8, v234, 22
	v_readlane_b32 s9, v234, 23
	s_add_u32 s42, s58, s8
	s_addc_u32 s43, s57, s9
	v_readlane_b32 s70, v234, 21
	s_bitcmp1_b32 s2, 0
	s_cbranch_scc0 .Lmy_g1ord
	s_add_u32 s42, s42, 0x800000
	s_addc_u32 s43, s43, 0
	s_add_i32 s70, s70, 16

.LBB0_192:
	s_add_i32 s63, s63, 1
	s_lshr_b32 s98, s63, 1
	s_lshr_b32 s99, s63, 2
	s_xor_b32 s98, s98, s99
	s_and_b32 s98, s98, 1
	s_mul_i32 s98, s98, 6
	s_xor_b32 s98, s63, s98
	s_and_b32 s99, s2, 1
	s_lshl_b32 s99, s99, 1
	s_xor_b32 s99, s98, s99
	s_mul_i32 s0, s99, s10
	s_add_i32 s0, s0, s2
	s_cmpk_gt_i32 s0, 0x7ff
	s_cselect_b64 s[46:47], -1, 0
	s_and_b64 vcc, exec, s[46:47]
	s_cbranch_vccnz .LBB0_198
	s_ashr_i32 s1, s0, 31
	s_lshr_b32 s1, s1, 29
	s_add_i32 s23, s0, s1
	s_and_b32 s1, s23, -8
	s_sub_i32 s24, s0, s1
	s_cmp_gt_i32 s24, -1
	s_mov_b64 s[0:1], -1
	s_cbranch_scc0 .LBB0_195
	s_lshl_b32 s25, s24, 8
	s_mov_b64 s[0:1], 0
